# v17 + P0 RMSNorm pass: wave sums via DPP/permlane swaps and next rows' loads issued one iteration ahead
# baseline (speedup 1.0000x reference)
; #define GAS __attribute__((address_space(1)))
; __device__ __forceinline__ void rms_rows2_to_bf16(const float* x, bf16* xn, float* rmsx, int m, int m2, int lane) {
;     const GAS f32x4* xa = (const GAS f32x4*)(x + (size_t)m * D) + lane; const GAS f32x4* xb = (const GAS f32x4*)(x + (size_t)m2 * D) + lane;
;     f32x4 va[4], vb[4]; float sa = 0.f, sb = 0.f;
; #pragma unroll
;     for (int j = 0; j < 4; ++j) { va[j] = __builtin_nontemporal_load(xa + 64 * j); vb[j] = __builtin_nontemporal_load(xb + 64 * j); }
; __global__ void __launch_bounds__(NWAVES * 64, 2) hymba_fwd(Args args) {
;     ...
;         for (int m = gw; m < M / 2; m += NGW) rms_rows2_to_bf16(x, XN, RMSX, m, m + M / 2, lane);
.LBB0_135:
	v_and_b32_e32 v158, 63, v175
	s_cmpk_gt_i32 s8, 0x3fff
	v_mbcnt_lo_u32_b32 v179, -1, 0
	v_lshlrev_b32_e32 v154, 3, v158
	s_cbranch_scc1 .LBB0_140
	v_mbcnt_hi_u32_b32 v2, -1, v179
	v_and_b32_e32 v1, 64, v2
	v_add_u32_e32 v3, 64, v1
	v_xor_b32_e32 v1, 1, v2
	v_cmp_lt_i32_e32 vcc, v1, v3
	v_xor_b32_e32 v4, 2, v2
	s_add_i32 s4, s8, 0x4000
	v_cndmask_b32_e32 v1, v2, v1, vcc
	v_cmp_lt_i32_e32 vcc, v4, v3
	s_ashr_i32 s5, s4, 31
	s_lshl_b64 s[6:7], s[4:5], 11
	v_cndmask_b32_e32 v4, v2, v4, vcc
	v_lshlrev_b32_e32 v40, 2, v4
	v_xor_b32_e32 v4, 4, v2
	v_cmp_lt_i32_e32 vcc, v4, v3
	s_ashr_i32 s11, s10, 31
	s_ashr_i32 s9, s8, 31
	v_cndmask_b32_e32 v4, v2, v4, vcc
	v_lshlrev_b32_e32 v41, 2, v4
	v_xor_b32_e32 v4, 8, v2
	v_cmp_lt_i32_e32 vcc, v4, v3
	v_or_b32_e32 v34, s6, v154
	v_mov_b32_e32 v35, s7
	v_cndmask_b32_e32 v4, v2, v4, vcc
	v_lshlrev_b32_e32 v42, 2, v4
	v_xor_b32_e32 v4, 16, v2
	v_cmp_lt_i32_e32 vcc, v4, v3
	s_lshl_b64 s[12:13], s[10:11], 11
	s_lshl_b64 s[6:7], s[8:9], 12
	v_cndmask_b32_e32 v4, v2, v4, vcc
	s_waitcnt lgkmcnt(0)
	s_add_u32 s14, s48, s6
	v_lshlrev_b32_e32 v43, 2, v4
	v_xor_b32_e32 v4, 32, v2
	s_addc_u32 s15, s49, s7
	s_lshl_b64 s[16:17], s[10:11], 12
	s_lshl_b64 s[4:5], s[4:5], 12
	v_cmp_lt_i32_e32 vcc, v4, v3
	s_add_u32 s18, s48, s4
	s_addc_u32 s19, s49, s5
	v_cndmask_b32_e32 v2, v2, v4, vcc
	s_lshl_b64 s[4:5], s[8:9], 11
	v_cmp_eq_u32_e64 s[0:1], 0, v158
	v_lshlrev_b32_e32 v1, 2, v1
	v_lshlrev_b32_e32 v44, 2, v2
	v_lshlrev_b32_e32 v36, 4, v158
	v_mov_b32_e32 v37, 0
	s_lshl_b64 s[20:21], s[8:9], 2
	s_lshl_b64 s[22:23], s[10:11], 2
	v_or_b32_e32 v38, s4, v154
	v_mov_b32_e32 v39, s5
	v_mov_b32_e32 v45, 0x358637bd
	s_mov_b32 s9, 0xf800000
	v_mov_b32_e32 v46, 0x260
	v_mov_b32_e32 v47, 0x1d00000
	v_mov_b32_e32 v48, 0x1d10000
	s_movk_i32 s11, 0x7fff
	s_mov_b32 s25, 0xffff0000
	s_mov_b32 s26, 0x16000000
	v_lshl_add_u64 v[98:99], s[14:15], 0, v[36:37]
	v_lshl_add_u64 v[102:103], s[18:19], 0, v[36:37]
	global_load_dwordx4 v[66:69], v[98:99], off nt
	global_load_dwordx4 v[70:73], v[102:103], off nt
	global_load_dwordx4 v[74:77], v[98:99], off offset:1024 nt
	global_load_dwordx4 v[78:81], v[102:103], off offset:1024 nt
	global_load_dwordx4 v[82:85], v[98:99], off offset:2048 nt
	global_load_dwordx4 v[86:89], v[102:103], off offset:2048 nt
	global_load_dwordx4 v[90:93], v[98:99], off offset:3072 nt
	global_load_dwordx4 v[94:97], v[102:103], off offset:3072 nt
	s_waitcnt vmcnt(0)
	s_branch .LBB0_138

; #define GAS __attribute__((address_space(1)))
; __device__ __forceinline__ void rms_rows2_to_bf16(const float* x, bf16* xn, float* rmsx, int m, int m2, int lane) {
;     const GAS f32x4* xa = (const GAS f32x4*)(x + (size_t)m * D) + lane; const GAS f32x4* xb = (const GAS f32x4*)(x + (size_t)m2 * D) + lane;
;     f32x4 va[4], vb[4]; float sa = 0.f, sb = 0.f;
; #pragma unroll
;     for (int j = 0; j < 4; ++j) { va[j] = __builtin_nontemporal_load(xa + 64 * j); vb[j] = __builtin_nontemporal_load(xb + 64 * j); }
; #pragma unroll
;     for (int j = 0; j < 4; ++j) { sa += (va[j].x * va[j].x + va[j].y * va[j].y) + (va[j].z * va[j].z + va[j].w * va[j].w); sb += (vb[j].x * vb[j].x + vb[j].y * vb[j].y) + (vb[j].z * vb[j].z + vb[j].w * vb[j].w); }
;     const float qa = sqrtf(wave_sum(sa) * (1.f / D) + EPS), qb = sqrtf(wave_sum(sb) * (1.f / D) + EPS); const float ra = 1.0f / qa, rb = 1.0f / qb;
;     if (lane == 0) { rmsx[m] = qa; rmsx[m2] = qb; }
.LBB0_138:
	s_waitcnt vmcnt(10)
	v_mov_b32_e32 v30, v66
	v_mov_b32_e32 v31, v67
	v_mov_b32_e32 v32, v68
	v_mov_b32_e32 v33, v69
	v_mov_b32_e32 v26, v70
	v_mov_b32_e32 v27, v71
	v_mov_b32_e32 v28, v72
	v_mov_b32_e32 v29, v73
	v_mov_b32_e32 v22, v74
	v_mov_b32_e32 v23, v75
	v_mov_b32_e32 v24, v76
	v_mov_b32_e32 v25, v77
	v_mov_b32_e32 v18, v78
	v_mov_b32_e32 v19, v79
	v_mov_b32_e32 v20, v80
	v_mov_b32_e32 v21, v81
	v_mov_b32_e32 v14, v82
	v_mov_b32_e32 v15, v83
	v_mov_b32_e32 v16, v84
	v_mov_b32_e32 v17, v85
	v_mov_b32_e32 v10, v86
	v_mov_b32_e32 v11, v87
	v_mov_b32_e32 v12, v88
	v_mov_b32_e32 v13, v89
	v_mov_b32_e32 v6, v90
	v_mov_b32_e32 v7, v91
	v_mov_b32_e32 v8, v92
	v_mov_b32_e32 v9, v93
	v_mov_b32_e32 v2, v94
	v_mov_b32_e32 v3, v95
	v_mov_b32_e32 v4, v96
	v_mov_b32_e32 v5, v97
	s_add_i32 s101, s8, s10
	s_cmpk_gt_i32 s101, 0x3fff
	s_cbranch_scc1 .Lp0_nopf
	v_lshl_add_u64 v[98:99], s[14:15], 0, v[36:37]
	v_lshl_add_u64 v[102:103], s[18:19], 0, v[36:37]
	v_lshl_add_u64 v[98:99], v[98:99], 0, s[16:17]
	v_lshl_add_u64 v[102:103], v[102:103], 0, s[16:17]
	global_load_dwordx4 v[66:69], v[98:99], off nt
	global_load_dwordx4 v[70:73], v[102:103], off nt
	global_load_dwordx4 v[74:77], v[98:99], off offset:1024 nt
	global_load_dwordx4 v[78:81], v[102:103], off offset:1024 nt
	global_load_dwordx4 v[82:85], v[98:99], off offset:2048 nt
	global_load_dwordx4 v[86:89], v[102:103], off offset:2048 nt
	global_load_dwordx4 v[90:93], v[98:99], off offset:3072 nt
	global_load_dwordx4 v[94:97], v[102:103], off offset:3072 nt
.Lp0_nopf:
	v_mul_f32_e32 v51, v27, v27
	v_mul_f32_e32 v52, v29, v29
	v_mul_f32_e32 v53, v23, v23
	v_mul_f32_e32 v54, v25, v25
	v_mul_f32_e32 v49, v31, v31
	v_mul_f32_e32 v50, v33, v33
	v_mul_f32_e32 v55, v19, v19
	v_mul_f32_e32 v56, v21, v21
	v_mul_f32_e32 v57, v15, v15
	v_mul_f32_e32 v58, v17, v17
	v_fmac_f32_e32 v49, v30, v30
	v_fmac_f32_e32 v50, v32, v32
	v_fmac_f32_e32 v51, v26, v26
	v_fmac_f32_e32 v52, v28, v28
	v_fmac_f32_e32 v53, v22, v22
	v_fmac_f32_e32 v54, v24, v24
	v_mul_f32_e32 v59, v11, v11
	v_mul_f32_e32 v60, v13, v13
	v_mul_f32_e32 v61, v7, v7
	v_mul_f32_e32 v62, v9, v9
	v_fmac_f32_e32 v55, v18, v18
	v_fmac_f32_e32 v56, v20, v20
	v_fmac_f32_e32 v57, v14, v14
	v_fmac_f32_e32 v58, v16, v16
	v_add_f32_e32 v49, v49, v50
	v_add_f32_e32 v50, v51, v52
	v_add_f32_e32 v51, v53, v54
	v_mul_f32_e32 v63, v3, v3
	v_mul_f32_e32 v64, v5, v5
	v_fmac_f32_e32 v59, v10, v10
	v_fmac_f32_e32 v60, v12, v12
	v_fmac_f32_e32 v61, v6, v6
	v_fmac_f32_e32 v62, v8, v8
	v_add_f32_e32 v52, v55, v56
	v_add_f32_e32 v53, v57, v58
	v_add_f32_e32 v49, v49, v51
	v_fmac_f32_e32 v63, v2, v2
	v_fmac_f32_e32 v64, v4, v4
	v_add_f32_e32 v54, v59, v60
	v_add_f32_e32 v55, v61, v62
	v_add_f32_e32 v50, v50, v52
	v_add_f32_e32 v49, v49, v53
	v_add_f32_e32 v56, v63, v64
	v_add_f32_e32 v50, v50, v54
	v_add_f32_e32 v49, v49, v55
	v_add_f32_e32 v50, v50, v56
	s_nop 0
	v_add_f32_dpp v49, v49, v49 quad_perm:[1,0,3,2] row_mask:0xf bank_mask:0xf
	s_nop 0
	v_add_f32_dpp v50, v50, v50 quad_perm:[1,0,3,2] row_mask:0xf bank_mask:0xf
	s_nop 0
	v_add_f32_dpp v49, v49, v49 quad_perm:[2,3,0,1] row_mask:0xf bank_mask:0xf
	s_nop 0
	v_add_f32_dpp v50, v50, v50 quad_perm:[2,3,0,1] row_mask:0xf bank_mask:0xf
	s_nop 0
	v_add_f32_dpp v49, v49, v49 row_half_mirror row_mask:0xf bank_mask:0xf
	s_nop 0
	v_add_f32_dpp v50, v50, v50 row_half_mirror row_mask:0xf bank_mask:0xf
	s_nop 0
	v_add_f32_dpp v49, v49, v49 row_mirror row_mask:0xf bank_mask:0xf
	s_nop 0
	v_add_f32_dpp v50, v50, v50 row_mirror row_mask:0xf bank_mask:0xf
	v_mov_b32_e32 v51, v49
	v_mov_b32_e32 v65, v49
	v_mov_b32_e32 v52, v50
	v_mov_b32_e32 v100, v50
	v_permlane16_swap_b32_e32 v51, v65
	s_nop 0
	v_permlane16_swap_b32_e32 v52, v100
	v_add_f32_e32 v49, v51, v65
	v_add_f32_e32 v50, v52, v100
	v_mov_b32_e32 v51, v49
	v_mov_b32_e32 v65, v49
	v_mov_b32_e32 v52, v50
	v_mov_b32_e32 v100, v50
	v_permlane32_swap_b32_e32 v51, v65
	s_nop 0
	v_permlane32_swap_b32_e32 v52, v100
	v_add_f32_e32 v49, v51, v65
	v_add_f32_e32 v50, v52, v100
	v_fmamk_f32 v49, v49, 0x3a800000, v45
	v_fmamk_f32 v50, v50, 0x3a800000, v45
	v_mul_f32_e32 v51, 0x4f800000, v49
	v_cmp_gt_f32_e32 vcc, s9, v49
	v_mul_f32_e32 v52, 0x4f800000, v50
	v_cmp_gt_f32_e64 s[4:5], s9, v50
	v_cndmask_b32_e32 v49, v49, v51, vcc
	v_sqrt_f32_e32 v51, v49
	v_cndmask_b32_e64 v50, v50, v52, s[4:5]
	v_sqrt_f32_e32 v52, v50
	v_add_u32_e32 v53, -1, v51
	v_fma_f32 v57, -v53, v51, v49
	v_add_u32_e32 v55, -1, v52
	v_add_u32_e32 v54, 1, v51
	v_fma_f32 v59, -v55, v52, v50
	v_cmp_ge_f32_e64 s[6:7], 0, v57
	v_add_u32_e32 v56, 1, v52
	v_fma_f32 v58, -v54, v51, v49
	v_cndmask_b32_e64 v51, v51, v53, s[6:7]
	v_cmp_ge_f32_e64 s[6:7], 0, v59
	v_fma_f32 v60, -v56, v52, v50
	s_nop 0
	v_cndmask_b32_e64 v52, v52, v55, s[6:7]
	v_cmp_lt_f32_e64 s[6:7], 0, v58
	s_nop 1
	v_cndmask_b32_e64 v51, v51, v54, s[6:7]
	v_cmp_lt_f32_e64 s[6:7], 0, v60
	v_mul_f32_e32 v53, 0x37800000, v51
	v_cndmask_b32_e32 v51, v51, v53, vcc
	v_cndmask_b32_e64 v52, v52, v56, s[6:7]
	v_mul_f32_e32 v54, 0x37800000, v52
	v_cmp_class_f32_e32 vcc, v49, v46
	v_cndmask_b32_e64 v52, v52, v54, s[4:5]
	s_nop 0
	v_cndmask_b32_e32 v49, v51, v49, vcc
	v_cmp_class_f32_e32 vcc, v50, v46
	s_nop 1
	v_cndmask_b32_e32 v50, v52, v50, vcc
	s_and_saveexec_b64 s[4:5], s[0:1]
	s_cbranch_execz .LBB0_137
	s_add_u32 s6, s70, s20
	s_addc_u32 s7, s71, s21
	global_store_dword v47, v49, s[6:7]
	global_store_dword v48, v50, s[6:7]
	s_branch .LBB0_137
